# odd workgroups run the weight conversion before the Fourier fold so the MFMA-bound fold overlaps the HBM-bound conversion
# speedup vs baseline: 1.0343x; 1.0010x over previous
; #define LAS __attribute__((address_space(3)))
; __device__ __forceinline__ void p0_fold(LAS unsigned char* lds, const float* w_mix_in, const float* w_fourier, unsigned char* wsW, int tid, int G) {
;     LAS float* tab = (LAS float*)lds;
;     LAS float* Mx = (LAS float*)(lds + 512);
;     LAS float* Wb = (LAS float*)(lds + 512 + 65536);
;     const int lane = tid & 63, wv = tid >> 6, r32 = lane & 31, hi = lane >> 5;
;     if (tid < 128) tab[tid] = cospif((float)tid * (1.f / 64.f)) * 0.08838834764831845f;
;     __syncthreads();
;     for (int w = blockIdx.x; w < 256; w += G) {
;         const int combo = w >> 3, l = combo >> 4, g = (combo >> 1) & 7, part = combo & 1;
;         const float* Wf = w_fourier + ((size_t)(l * 8 + g) * 128) * 128;
;         { f32x16 acc[2];
; #pragma unroll
;           for (int tt = 0; tt < 2; ++tt)
; #pragma unroll
;               for (int i = 0; i < 16; ++i) acc[tt][i] = 0.f;
;           for (int half = 0; half < 2; ++half) {
; #pragma unroll
;               for (int q = 0; q < 4; ++q) { const int i = tid + 512 * q, kk = i >> 5, c4 = i & 31;
;                   *(LAS f32x4*)(Wb + kk * 128 + 4 * c4) = *(const f32x4*)(Wf + (size_t)(64 * half + kk) * 128 + 4 * c4); }
;               __syncthreads();
; #pragma unroll
;               for (int tt = 0; tt < 2; ++tt) { const int tile = wv * 2 + tt, tc = tile >> 2, te = tile & 3, c = tc * 32 + r32, e = te * 32 + r32;
; #pragma unroll 8
;                   for (int kk = 0; kk < 32; ++kk) { const int kl = 2 * kk + hi, k2 = 64 * half + kl;
;                       acc[tt] = __builtin_amdgcn_mfma_f32_32x32x2f32(tab[(k2 * c - (part ? 32 : 0)) & 127], Wb[kl * 128 + e], acc[tt], 0, 0, 0); } }
.LBB0_31:
	s_or_b64 exec, exec, s[0:1]
	v_readlane_b32 s12, v255, 3
	v_readlane_b32 s26, v255, 17
	v_readlane_b32 s27, v255, 18
	s_add_u32 s3, s26, 0x4800000
	v_cndmask_b32_e64 v2, 0, 1, s[6:7]
	s_addc_u32 s8, s27, 0
	v_cmp_ne_u32_e64 s[0:1], 1, v2
	s_andn2_b64 vcc, exec, s[6:7]
	v_readlane_b32 s13, v255, 4
	v_readlane_b32 s14, v255, 5
	v_readlane_b32 s15, v255, 6
	v_readlane_b32 s16, v255, 7
	v_readlane_b32 s17, v255, 8
	v_readlane_b32 s18, v255, 9
	v_readlane_b32 s19, v255, 10
	v_readlane_b32 s20, v255, 11
	v_readlane_b32 s21, v255, 12
	v_readlane_b32 s22, v255, 13
	v_readlane_b32 s23, v255, 14
	v_readlane_b32 s24, v255, 15
	v_readlane_b32 s25, v255, 16
	s_waitcnt lgkmcnt(0)
	s_barrier
	s_bitcmp0_b32 s9, 0
	s_cbranch_scc1 .Lp0_resume_fold
	v_mov_b32_e32 v48, v0
	v_mov_b32_e32 v49, v1
	v_writelane_b32 v51, s0, 0
	v_writelane_b32 v51, s1, 1
	v_writelane_b32 v51, s5, 2
	v_writelane_b32 v51, s13, 3
	v_writelane_b32 v51, s28, 4
	v_writelane_b32 v51, s29, 5
	v_writelane_b32 v51, s30, 6
	v_writelane_b32 v51, s31, 7
	v_writelane_b32 v51, s51, 8
	v_writelane_b32 v51, s53, 9
	v_writelane_b32 v51, s55, 10
	s_lshl_b32 s0, s9, 3
	v_readlane_b32 s1, v255, 21
	s_lshl_b32 s5, s72, 3
	s_nop 1
	s_add_i32 s4, s0, s1
	v_writelane_b32 v255, s5, 22
	v_writelane_b32 v255, s1, 23
	v_writelane_b32 v255, s4, 24
	v_writelane_b32 v255, s1, 25
	s_branch .Lp0_weights_entry
.Lp0_resume_fold:
	s_cbranch_vccnz .LBB0_50
	v_and_b32_e32 v2, 0x7c, v50
	v_lshlrev_b32_e32 v56, 2, v2
	s_add_i32 s4, 0, 0x10200
	v_and_b32_e32 v3, 31, v0
	v_add_u32_e32 v9, s4, v56
	v_lshrrev_b32_e32 v2, 2, v0
	s_movk_i32 s4, 0x60
	v_and_or_b32 v65, v2, s4, v3
	v_lshrrev_b32_e32 v2, 1, v0
	v_and_or_b32 v82, v2, s4, v3
	v_lshrrev_b32_e32 v2, 3, v0
	v_and_b32_e32 v2, 32, v2
	v_bfe_u32 v51, v0, 5, 1
	v_lshlrev_b32_e32 v5, 2, v3
	v_or_b32_e32 v14, v2, v3
	s_movk_i32 s4, 0x600
	v_lshlrev_b32_e32 v3, 4, v3
	v_and_or_b32 v84, v50, s4, v3
	v_or_b32_e32 v3, 14, v51
	v_add_u32_e32 v7, 0, v5
	v_and_b32_e32 v11, 0x100, v50
	v_lshlrev_b32_e32 v13, 11, v51
	v_mul_u32_u24_e32 v85, v65, v3
	v_lshlrev_b32_e32 v3, 9, v51
	v_add3_u32 v7, v7, v13, v11
	v_or3_b32 v11, v3, v11, v5
	v_add_u32_e32 v86, 0, v11
	v_or_b32_e32 v11, 12, v51
	v_mul_u32_u24_e32 v87, v65, v11
	v_or_b32_e32 v11, 2, v51
	v_mul_u32_u24_e32 v88, v65, v11
	v_or_b32_e32 v11, 10, v51
	v_mul_u32_u24_e32 v89, v65, v11
	v_or_b32_e32 v11, 8, v51
	v_mul_u32_u24_e32 v90, v65, v11
	v_or_b32_e32 v11, 6, v51
	v_mul_u32_u24_e32 v91, v65, v11
	v_or_b32_e32 v11, 4, v51
	v_lshrrev_b32_e32 v54, 5, v0
	v_or_b32_e32 v8, 0x200, v0
	v_or_b32_e32 v12, 0x600, v0
	v_mul_u32_u24_e32 v92, v65, v11
	v_lshlrev_b32_e32 v11, 1, v0
	v_lshrrev_b32_e32 v62, 5, v8
	v_or_b32_e32 v64, 32, v54
	v_lshrrev_b32_e32 v66, 5, v12
	v_lshlrev_b32_e32 v19, 7, v0
	v_and_b32_e32 v11, 0x180, v11
	v_mov_b32_e32 v57, 0
	v_lshlrev_b32_e32 v4, 2, v51
	v_lshlrev_b32_e32 v6, 7, v54
	v_lshlrev_b32_e32 v15, 9, v54
	v_lshlrev_b32_e32 v8, 7, v62
	v_lshlrev_b32_e32 v16, 9, v62
	v_lshlrev_b32_e32 v10, 7, v64
	v_lshlrev_b32_e32 v17, 9, v64
	v_lshlrev_b32_e32 v12, 7, v66
	v_lshlrev_b32_e32 v18, 9, v66
	v_and_b32_e32 v19, 0xc000, v19
	s_movk_i32 s6, 0x204
	v_mul_u32_u24_e32 v13, 0x204, v54
	v_mul_u32_u24_e32 v20, 0x204, v62
	v_mul_u32_u24_e32 v21, 0x204, v66
	v_or3_b32 v3, v3, v11, v5
	s_mov_b32 s5, 0
	v_lshl_add_u64 v[58:59], s[50:51], 0, v[56:57]
	v_lshl_add_u64 v[60:61], s[48:49], 0, v[56:57]
	v_mov_b32_e32 v67, v57
	v_mul_u32_u24_e32 v83, v65, v51
	v_add_u32_e32 v93, 0x200, v3
	v_mad_u32_u24 v94, v14, s6, v4
	v_lshlrev_b32_e32 v68, 2, v6
	v_lshlrev_b32_e32 v70, 2, v8
	v_lshlrev_b32_e32 v72, 2, v10
	v_lshlrev_b32_e32 v56, 2, v12
	v_add_u32_e32 v95, v7, v19
	v_lshlrev_b32_e32 v74, 1, v2
	v_lshlrev_b32_e32 v76, 1, v4
	s_mov_b64 s[6:7], 0x8400000
	s_mov_b32 s10, 0x8400000
	v_mov_b32_e32 v69, v57
	v_add_u32_e32 v96, v9, v15
	v_mov_b32_e32 v71, v57
	v_add_u32_e32 v97, v9, v16
	v_mov_b32_e32 v73, v57
	v_add_u32_e32 v98, v9, v17
	v_add_u32_e32 v99, v9, v18
	v_add_u32_e32 v100, v9, v13
	v_add_u32_e32 v101, v9, v20
	v_add_u32_e32 v102, v9, v21
	v_readlane_b32 s11, v255, 2

; #define LAS __attribute__((address_space(3)))
; __device__ __forceinline__ void p0_weights(LAS unsigned char* lds, const float* const* in, unsigned char* wsW, int gw, int NGW, int wave, int lane) {
;     LAS float* scr = (LAS float*)(lds + wave * 16384);
;     for (int it = gw; it < 2 * IT_LAYER; it += NGW) {
;         const int l = it / IT_LAYER; int r = it % IT_LAYER; unsigned char* wl = wsW + (size_t)l * W_LAYER;
;         if (r < 2 * IT_GU) { const int f = r / IT_GU; r %= IT_GU; const int nblk = 2 * FF / 32, kb = r / nblk, nb = r % nblk, n0 = 32 * nb;
;             const int j0 = n0 < FF ? n0 : n0 - FF, drow = (j0 >> 7) * 256 + (n0 < FF ? 0 : 128) + (j0 & 127);
;             tr_item(in[f ? 11 : 4] + (size_t)l * DM * 2 * FF, 2 * FF, 64 * kb, n0, (bf16*)(wl + (f ? W_GU2 : W_GU1)), DM, drow, 64 * kb, nullptr, scr, lane); continue; }
.LBB0_61:
	s_lshl_b32 s0, s9, 3
	v_readlane_b32 s1, v255, 21
	s_add_i32 s4, s0, s1
	s_lshl_b32 s0, s72, 3
	v_writelane_b32 v255, s0, 22
	s_cmp_gt_i32 s4, 0x12fff
	s_nop 0
	v_writelane_b32 v255, s1, 23
	s_mov_b32 s0, s4
	v_writelane_b32 v255, s0, 24
	s_barrier
	s_nop 0
	v_writelane_b32 v255, s1, 25
	s_cbranch_scc1 .LBB0_95
	s_bitcmp1_b32 s9, 0
	s_cbranch_scc1 .Lp0_weights_exit
.Lp0_weights_entry:
	v_lshrrev_b32_e32 v40, 3, v55
	v_and_b32_e32 v41, 7, v55
	v_readlane_b32 s5, v255, 21
	v_readlane_b32 s30, v255, 22
	v_readlane_b32 s20, v255, 9
	v_readlane_b32 s21, v255, 10
	v_readlane_b32 s22, v255, 11
	v_readlane_b32 s23, v255, 12
	v_readlane_b32 s24, v255, 7
	v_readlane_b32 s25, v255, 8
	v_readlane_b32 s26, v255, 3
	v_readlane_b32 s27, v255, 4
	v_readlane_b32 s28, v255, 5
	v_readlane_b32 s29, v255, 6
	v_lshlrev_b32_e32 v44, 2, v40
	v_lshlrev_b32_e32 v43, 4, v41
	s_lshl_b32 s5, s5, 14
	s_addk_i32 s5, 0x200
	v_mul_u32_u24_e32 v42, 0x84, v40
	v_mul_u32_u24_e32 v45, 0x420, v41
	v_add3_u32 v42, v42, v43, s5
	v_add3_u32 v45, v45, v44, s5
	s_mov_b32 s51, s4

; __device__ __forceinline__ void p0_weights(LAS unsigned char* lds, const float* const* in, unsigned char* wsW, int gw, int NGW, int wave, int lane) {
;     ...
;     for (int it = gw; it < 2 * IT_LAYER; it += NGW) {
;         const int l = it / IT_LAYER; int r = it % IT_LAYER; unsigned char* wl = wsW + (size_t)l * W_LAYER;
;         if (r < 2 * IT_GU) { const int f = r / IT_GU; r %= IT_GU; const int nblk = 2 * FF / 32, kb = r / nblk, nb = r % nblk, n0 = 32 * nb;
;             const int j0 = n0 < FF ? n0 : n0 - FF, drow = (j0 >> 7) * 256 + (n0 < FF ? 0 : 128) + (j0 & 127);
;             tr_item(in[f ? 11 : 4] + (size_t)l * DM * 2 * FF, 2 * FF, 64 * kb, n0, (bf16*)(wl + (f ? W_GU2 : W_GU1)), DM, drow, 64 * kb, nullptr, scr, lane); continue; }
	s_cmp_ge_u32 s51, 0x9800
	s_cselect_b32 s10, 1, 0
	s_mul_i32 s11, s10, 0x9800
	s_sub_u32 s11, s51, s11
	s_mul_i32 s12, s10, 0xa000000
	s_add_u32 s66, s3, s12
	s_addc_u32 s67, s8, 0
	s_mov_b32 s69, 0
	s_cmp_lt_u32 s11, 0x5800
	s_cbranch_scc0 .Lpw_notgu_a
	s_cmp_ge_u32 s11, 0x2c00
	s_cselect_b32 s13, 1, 0
	s_cselect_b32 s60, s20, s44
	s_cselect_b32 s61, s21, s45
	s_mul_i32 s14, s13, 0x2c00
	s_sub_u32 s11, s11, s14
	s_mul_hi_u32 s15, s11, 0xba2e8c
	s_mul_i32 s14, s15, 0x160
	s_sub_u32 s16, s11, s14
	s_lshl_b32 s16, s16, 5
	s_mul_i32 s14, s10, 0x5800000
	s_add_u32 s60, s60, s14
	s_addc_u32 s61, s61, 0
	s_mul_i32 s14, s15, 0x2c0000
	s_add_u32 s60, s60, s14
	s_addc_u32 s61, s61, 0
	s_lshl_b32 s14, s16, 2
	s_add_u32 s60, s60, s14
	s_addc_u32 s61, s61, 0
	s_mov_b32 s62, 0xb000
	s_mov_b32 s63, 0x58000
	s_cmp_ge_u32 s16, 0x1600
	s_cselect_b32 s17, 1, 0
	s_mul_i32 s18, s17, 0x1600
	s_sub_u32 s18, s16, s18
	s_lshr_b32 s19, s18, 7
	s_lshl_b32 s19, s19, 8
	s_lshl_b32 s14, s17, 7
	s_add_u32 s19, s19, s14
	s_and_b32 s14, s18, 0x7f
	s_add_u32 s19, s19, s14
	s_mul_i32 s14, s13, 0x2c00000
	s_add_u32 s66, s66, s14
	s_addc_u32 s67, s67, 0
	s_lshl_b32 s14, s19, 12
	s_add_u32 s66, s66, s14
	s_addc_u32 s67, s67, 0
	s_lshl_b32 s14, s15, 7
	s_add_u32 s66, s66, s14
	s_addc_u32 s67, s67, 0
	s_movk_i32 s68, 0x1000
	s_mov_b32 s70, 0x8000
	s_branch .Lpw_pdone_a

; #define LAS __attribute__((address_space(3)))
; #define LDS_WAIT() asm volatile("s_waitcnt lgkmcnt(0)" ::: "memory")
; __device__ __forceinline__ unsigned pk2(float lo, float hi) { f32x2_t v = {lo, hi}; bf16x2_t b = __builtin_convertvector(v, bf16x2_t); return __builtin_bit_cast(unsigned, b); }
; __device__ __forceinline__ void tr_item(const float* W, int ldw, int k0, int n0src, bf16* WT, int ldt, int drow0, int dk0, const float* gain, LAS float* scr, int lane) {
;     ...
;     LDS_WAIT(); asm volatile("" ::: "memory");
;     const int c = lane & 7;
; #pragma unroll
;     for (int j = 0; j < 4; ++j) { const int n = (lane >> 3) + 8 * j; const LAS float* s = scr + (8 * c) * 33 + n;
;         v4u o; o.x = pk2(s[0 * 33], s[1 * 33]); o.y = pk2(s[2 * 33], s[3 * 33]); o.z = pk2(s[4 * 33], s[5 * 33]); o.w = pk2(s[6 * 33], s[7 * 33]);
;         *(v4u*)(WT + (size_t)(drow0 + n) * ldt + dk0 + 8 * c) = o; }
;     LDS_WAIT(); asm volatile("" ::: "memory");
; }
.Lpw_last:
	s_waitcnt lgkmcnt(0)
	ds_read2_b32 v[64:65], v45 offset0:0 offset1:33
	ds_read2_b32 v[66:67], v45 offset0:66 offset1:99
	ds_read2_b32 v[68:69], v45 offset0:132 offset1:165
	ds_read2_b32 v[70:71], v45 offset0:198 offset1:231
	ds_read2_b32 v[72:73], v45 offset0:8 offset1:41
	ds_read2_b32 v[74:75], v45 offset0:74 offset1:107
	ds_read2_b32 v[76:77], v45 offset0:140 offset1:173
	ds_read2_b32 v[78:79], v45 offset0:206 offset1:239
	ds_read2_b32 v[80:81], v45 offset0:16 offset1:49
	ds_read2_b32 v[82:83], v45 offset0:82 offset1:115
	ds_read2_b32 v[84:85], v45 offset0:148 offset1:181
	ds_read2_b32 v[86:87], v45 offset0:214 offset1:247
	ds_read2_b32 v[88:89], v45 offset0:24 offset1:57
	ds_read2_b32 v[90:91], v45 offset0:90 offset1:123
	ds_read2_b32 v[92:93], v45 offset0:156 offset1:189
	ds_read2_b32 v[94:95], v45 offset0:222 offset1:255
	v_mad_u32_u24 v47, v40, s54, v43
	s_waitcnt lgkmcnt(0)
	v_cvt_pk_bf16_f32 v64, v64, v65
	v_cvt_pk_bf16_f32 v65, v66, v67
	v_cvt_pk_bf16_f32 v66, v68, v69
	v_cvt_pk_bf16_f32 v67, v70, v71
	v_cvt_pk_bf16_f32 v72, v72, v73
	v_cvt_pk_bf16_f32 v73, v74, v75
	v_cvt_pk_bf16_f32 v74, v76, v77
	v_cvt_pk_bf16_f32 v75, v78, v79
	v_cvt_pk_bf16_f32 v80, v80, v81
	v_cvt_pk_bf16_f32 v81, v82, v83
	v_cvt_pk_bf16_f32 v82, v84, v85
	v_cvt_pk_bf16_f32 v83, v86, v87
	v_cvt_pk_bf16_f32 v88, v88, v89
	v_cvt_pk_bf16_f32 v89, v90, v91
	v_cvt_pk_bf16_f32 v90, v92, v93
	v_cvt_pk_bf16_f32 v91, v94, v95
	global_store_dwordx4 v47, v[64:67], s[52:53]
	v_add_u32_e32 v47, s55, v47
	global_store_dwordx4 v47, v[72:75], s[52:53]
	v_add_u32_e32 v47, s55, v47
	global_store_dwordx4 v47, v[80:83], s[52:53]
	v_add_u32_e32 v47, s55, v47
	global_store_dwordx4 v47, v[88:91], s[52:53]
	s_bitcmp0_b32 s9, 0
	s_cbranch_scc1 .Lp0_weights_exit
	v_mov_b32_e32 v0, v48
	v_mov_b32_e32 v1, v49
	v_readlane_b32 s0, v51, 0
	v_readlane_b32 s1, v51, 1
	v_readlane_b32 s5, v51, 2
	v_readlane_b32 s13, v51, 3
	v_readlane_b32 s28, v51, 4
	v_readlane_b32 s29, v51, 5
	v_readlane_b32 s30, v51, 6
	v_readlane_b32 s31, v51, 7
	v_readlane_b32 s51, v51, 8
	v_readlane_b32 s53, v51, 9
	v_readlane_b32 s55, v51, 10
	s_barrier
	s_branch .Lp0_resume_fold
.Lp0_weights_exit:
	v_readlane_b32 s0, v255, 22
	v_readlane_b32 s1, v255, 23
